# attention phase: one static s_setprio 1 for the younger wave half (waves 4-7), reset at phase end; on top of the 2-DMA K-loop move
# speedup vs baseline: 1.0052x; 1.0052x over previous
; #define LAS __attribute__((address_space(3)))
; __global__ void __launch_bounds__(NWAVES * 64, 2) mega_fwd(Args args) {
;     ...
;     if (IN(5)) {
;         LAS float* tbl = (LAS float*)(ldsl + ATT_TBL_OFF);
;         { float tv[12];
; #pragma unroll
;           for (int j = 0; j < 12; ++j) { const int i = tid + j * (NWAVES * 64); const int h = i / 768, rel = (i % 768) - 383; const int ar = rel < 0 ? -rel : rel;
;               tv[j] = (ar <= 128) ? args.in[16][t5_bucket(rel) * 8 + h] * LOG2E : -1e30f; }
; #pragma unroll
;           for (int j = 0; j < 12; ++j) tbl[tid + j * (NWAVES * 64)] = tv[j]; }
.LBB0_425:
	s_or_b64 exec, exec, s[0:1]
	s_cmp_lt_i32 s30, 6
	s_cselect_b64 s[0:1], -1, 0
	s_cmp_gt_i32 s31, 5
	s_cselect_b64 s[2:3], -1, 0
	s_and_b64 s[0:1], s[0:1], s[2:3]
	s_andn2_b64 vcc, exec, s[0:1]
	s_waitcnt lgkmcnt(0)
	s_barrier
	s_cbranch_vccnz .LBB0_675
	v_readfirstlane_b32 s98, v230
	s_cmpk_lt_u32 s98, 0x100
	s_cbranch_scc1 .Lprio_p5_skip
	s_setprio 1
.Lprio_p5_skip:
	v_mul_hi_u32_u24_e32 v1, 0x555556, v230
	v_mul_u32_u24_e32 v0, 0x300, v1
	v_sub_u32_e32 v2, v230, v0
	v_min_u32_e32 v0, 0x17f, v2
	v_max_u32_e32 v3, 0x17f, v2
	v_sub_u32_e32 v0, v3, v0
	s_movk_i32 s0, 0x81
	v_cmp_gt_u32_e32 vcc, s0, v0
	v_mov_b32_e32 v0, 0xf149f2ca
	s_and_saveexec_b64 s[0:1], vcc
	s_cbranch_execz .LBB0_430
	v_add_u32_e32 v3, 0xfffffe81, v2
	v_sub_u32_e32 v0, 0, v3
	v_max_i32_e32 v0, v3, v0
	v_cmp_lt_u32_e32 vcc, 7, v0
	s_and_saveexec_b64 s[2:3], vcc
	v_mul_lo_u32 v0, v3, v3
	v_lshrrev_b32_e32 v0, 6, v0
	v_ffbh_u32_e32 v0, v0
	v_sub_u32_e32 v0, 39, v0
	v_min_u32_e32 v0, 15, v0
	s_or_b64 exec, exec, s[2:3]
	s_movk_i32 s2, 0x17f
	v_cmp_lt_u32_e32 vcc, s2, v2
	s_nop 1
	v_cndmask_b32_e64 v2, 0, 16, vcc
	v_or_b32_e32 v0, v0, v2
	v_lshl_or_b32 v0, v0, 3, v1
	v_mov_b32_e32 v1, 0
	v_lshl_add_u64 v[0:1], v[0:1], 2, s[52:53]
	global_load_dword v0, v[0:1], off
	s_waitcnt vmcnt(0)
	v_mul_f32_e32 v0, 0x3fb8aa3b, v0

.LBB0_672:
	v_max_f32_e32 v66, v66, v66
	v_max_f32_e32 v66, 0, v66
	v_exp_f32_e64 v67, -v66
	v_add_f32_e32 v213, v213, v66
	v_xor_b32_e32 v80, 0x80000000, v213
	v_mov_b32_e32 v81, v80
	v_mov_b32_e32 v82, v80
	v_mov_b32_e32 v83, v80
	v_mov_b32_e32 v84, v80
	v_mov_b32_e32 v85, v80
	v_mov_b32_e32 v86, v80
	v_mov_b32_e32 v87, v80
	v_mov_b32_e32 v88, v80
	v_mov_b32_e32 v89, v80
	v_mov_b32_e32 v90, v80
	v_mov_b32_e32 v91, v80
	v_mov_b32_e32 v92, v80
	v_mov_b32_e32 v93, v80
	v_mov_b32_e32 v94, v80
	v_mov_b32_e32 v95, v80
	s_and_saveexec_b64 s[36:37], s[2:3]
	ds_write_b32 v217, v67 offset:49152
	s_or_b64 exec, exec, s[36:37]
	v_sub_f32_e32 v64, v64, v66
	v_sub_f32_e32 v65, v65, v66
	v_sub_f32_e32 v48, v48, v66
	v_sub_f32_e32 v49, v49, v66
	v_sub_f32_e32 v68, v68, v66
	v_sub_f32_e32 v69, v69, v66
	v_sub_f32_e32 v70, v70, v66
	v_sub_f32_e32 v71, v71, v66
	v_sub_f32_e32 v72, v72, v66
	v_sub_f32_e32 v73, v73, v66
	v_sub_f32_e32 v74, v74, v66
	v_sub_f32_e32 v75, v75, v66
	v_sub_f32_e32 v76, v76, v66
	v_sub_f32_e32 v77, v77, v66
	v_sub_f32_e32 v78, v78, v66
	v_sub_f32_e32 v79, v79, v66
	v_sub_f32_e32 v14, v14, v66
	v_sub_f32_e32 v15, v15, v66
	v_sub_f32_e32 v50, v50, v66
	v_sub_f32_e32 v51, v51, v66
	v_sub_f32_e32 v52, v52, v66
	v_sub_f32_e32 v53, v53, v66
	v_sub_f32_e32 v54, v54, v66
	v_sub_f32_e32 v55, v55, v66
	v_sub_f32_e32 v56, v56, v66
	v_sub_f32_e32 v57, v57, v66
	v_sub_f32_e32 v58, v58, v66
	v_sub_f32_e32 v59, v59, v66
	v_sub_f32_e32 v60, v60, v66
	v_sub_f32_e32 v61, v61, v66
	v_sub_f32_e32 v62, v62, v66
	v_sub_f32_e32 v63, v63, v66
	v_mul_f32_e32 v1, v1, v67
	s_branch .LBB0_668
	s_setprio 0

; __global__ void __launch_bounds__(NWAVES * 64, 2) mega_fwd(Args args) {
	.amdhsa_kernel _Z8mega_fwd4Args
		.amdhsa_group_segment_fixed_size 0
		.amdhsa_private_segment_fixed_size 0
		.amdhsa_kernarg_size 424
		.amdhsa_user_sgpr_count 2
		.amdhsa_user_sgpr_dispatch_ptr 0
		.amdhsa_user_sgpr_queue_ptr 0
		.amdhsa_user_sgpr_kernarg_segment_ptr 1
		.amdhsa_user_sgpr_dispatch_id 0
		.amdhsa_user_sgpr_kernarg_preload_length 0
		.amdhsa_user_sgpr_kernarg_preload_offset 0
		.amdhsa_user_sgpr_private_segment_size 0
		.amdhsa_uses_dynamic_stack 0
		.amdhsa_enable_private_segment 0
		.amdhsa_system_sgpr_workgroup_id_x 1
		.amdhsa_system_sgpr_workgroup_id_y 0
		.amdhsa_system_sgpr_workgroup_id_z 0
		.amdhsa_system_sgpr_workgroup_info 0
		.amdhsa_system_vgpr_workitem_id 2
		.amdhsa_next_free_vgpr 256
		.amdhsa_next_free_sgpr 99
		.amdhsa_accum_offset 256
		.amdhsa_reserve_vcc 1
		.amdhsa_float_round_mode_32 0
		.amdhsa_float_round_mode_16_64 0
		.amdhsa_float_denorm_mode_32 3
		.amdhsa_float_denorm_mode_16_64 3
		.amdhsa_dx10_clamp 1
		.amdhsa_ieee_mode 1
		.amdhsa_fp16_overflow 0
		.amdhsa_tg_split 0
		.amdhsa_exception_fp_ieee_invalid_op 0
		.amdhsa_exception_fp_denorm_src 0
		.amdhsa_exception_fp_ieee_div_zero 0
		.amdhsa_exception_fp_ieee_overflow 0
		.amdhsa_exception_fp_ieee_underflow 0
		.amdhsa_exception_fp_ieee_inexact 0
		.amdhsa_exception_int_div_zero 0
	.end_amdhsa_kernel
